# scan compute: no per-step v scaling (zeroed LDS region for transfer rows), c1/c2 fetched for two steps per LDS read
# baseline (speedup 1.0000x reference)
.LBB0_663:
	v_readlane_b32 s24, v254, 49
	s_and_b64 vcc, exec, s[0:1]
	v_readlane_b32 s25, v254, 50
	s_cbranch_vccz .LBB0_679
	s_cmp_lg_u32 s15, 1
	s_mov_b64 s[0:1], -1
	s_cbranch_scc0 .LBB0_675
	v_and_b32_e32 v41, 15, v37
	v_lshrrev_b32_e32 v42, 4, v37
	v_readlane_b32 s2, v253, 12
	v_lshlrev_b32_e32 v43, 2, v41
	v_and_b32_e32 v45, 8, v37
	v_lshlrev_b32_e32 v46, 4, v41
	v_cmp_eq_u32_e64 s[6:7], 0, v45
	v_lshl_add_u32 v42, v42, 1, s2
	v_sub_u32_e32 v44, v42, v43
	v_lshlrev_b32_e32 v47, 2, v42
	v_add_u32_e32 v47, 0x5000, v47
	s_lshl_b32 s1, s14, 13
	s_add_i32 s1, s1, 0x18200
	v_lshl_add_u32 v48, v37, 2, s1
	v_lshlrev_b32_e32 v49, 8, v42
	v_lshl_add_u32 v49, v41, 4, v49
	s_cmp_eq_u32 s14, 0
	s_cselect_b32 s3, 0, 0xc100
	s_cmp_eq_u32 s14, 2
	s_cselect_b32 s4, 0, -1
	s_cbranch_scc0 .Lsc_vz_done
	v_lshlrev_b32_e32 v47, 2, v42
	v_mov_b32_e32 v44, 0
	v_add_u32_e32 v47, 0x1f000, v47
	v_mov_b32_e32 v45, 0
	ds_write_b64 v47, v[44:45] offset:0
	ds_write_b64 v47, v[44:45] offset:256
	ds_write_b64 v47, v[44:45] offset:512
	ds_write_b64 v47, v[44:45] offset:768
	ds_write_b64 v47, v[44:45] offset:1024
	ds_write_b64 v47, v[44:45] offset:1280
	ds_write_b64 v47, v[44:45] offset:1536
	ds_write_b64 v47, v[44:45] offset:1792
	ds_write_b64 v47, v[44:45] offset:2048
	ds_write_b64 v47, v[44:45] offset:2304
	ds_write_b64 v47, v[44:45] offset:2560
	ds_write_b64 v47, v[44:45] offset:2816
	ds_write_b64 v47, v[44:45] offset:3072
	ds_write_b64 v47, v[44:45] offset:3328
	ds_write_b64 v47, v[44:45] offset:3584
	ds_write_b64 v47, v[44:45] offset:3840
.Lsc_vz_done:
	v_sub_u32_e32 v44, v42, v43
	v_mov_b32_e32 v8, 0
	v_mov_b32_e32 v9, 0
	v_cmp_eq_u32_e32 vcc, 0, v44
	s_nop 1
	v_cndmask_b32_e64 v0, 0, 1.0, vcc
	v_cmp_eq_u32_e32 vcc, 1, v44
	s_nop 1
	v_cndmask_b32_e64 v1, 0, 1.0, vcc
	v_cmp_eq_u32_e32 vcc, 2, v44
	s_nop 1
	v_cndmask_b32_e64 v2, 0, 1.0, vcc
	v_cmp_eq_u32_e32 vcc, 3, v44
	s_nop 1
	v_cndmask_b32_e64 v3, 0, 1.0, vcc
	v_cmp_eq_u32_e32 vcc, -1, v44
	s_nop 1
	v_cndmask_b32_e64 v4, 0, 1.0, vcc
	v_cmp_eq_u32_e32 vcc, 0, v44
	s_nop 1
	v_cndmask_b32_e64 v5, 0, 1.0, vcc
	v_cmp_eq_u32_e32 vcc, 1, v44
	s_nop 1
	v_cndmask_b32_e64 v6, 0, 1.0, vcc
	v_cmp_eq_u32_e32 vcc, 2, v44
	s_nop 1
	v_cndmask_b32_e64 v7, 0, 1.0, vcc
	s_cmp_eq_u32 s14, 2
	s_cbranch_scc1 .Lsc_init_done
	v_mov_b32_e32 v0, 0
	v_mov_b32_e32 v1, 0
	v_mov_b32_e32 v2, 0
	v_mov_b32_e32 v3, 0
	v_mov_b32_e32 v4, 0
	v_mov_b32_e32 v5, 0
	v_mov_b32_e32 v6, 0
	v_mov_b32_e32 v7, 0

.Lsc_chunk:
	s_and_b32 s1, s0, 1
	s_lshl_b32 s2, s1, 12
	s_mulk_i32 s1, 0x6080
	s_add_i32 s1, s1, s3
	v_add_u32_e32 v10, s1, v46
	s_and_b32 s5, s1, s4
	v_add_u32_e32 v11, s5, v47
	v_add_u32_e32 v13, s2, v48
	s_add_i32 s1, s1, 0x6000
	v_mov_b32_e32 v12, s1
	ds_read_b128 v[52:55], v10 offset:0
	ds_read_b64 v[72:73], v11 offset:0
	ds_read_b128 v[64:67], v10 offset:12288
	ds_read_b128 v[60:63], v10 offset:8192
	ds_read_b128 v[56:59], v10 offset:4096
	ds_read_b128 v[68:71], v10 offset:16384
	ds_read_b128 v[124:127], v12 offset:0
	ds_read_b128 v[76:79], v10 offset:256
	ds_read_b64 v[96:97], v11 offset:256
	ds_read_b128 v[88:91], v10 offset:12544
	ds_read_b128 v[84:87], v10 offset:8448
	ds_read_b128 v[80:83], v10 offset:4352
	ds_read_b128 v[92:95], v10 offset:16640
	s_waitcnt lgkmcnt(6)
	ds_read_b128 v[100:103], v10 offset:512
	ds_read_b64 v[120:121], v11 offset:512
	ds_read_b128 v[112:115], v10 offset:12800
	ds_read_b128 v[108:111], v10 offset:8704
	ds_read_b128 v[104:107], v10 offset:4608
	ds_read_b128 v[116:119], v10 offset:16896
	ds_read_b128 v[128:131], v12 offset:16
	v_pk_mul_f32 v[16:17], v[0:1], v[52:53]
	v_pk_mul_f32 v[18:19], v[4:5], v[52:53]
	v_pk_fma_f32 v[16:17], v[2:3], v[54:55], v[16:17]
	v_pk_fma_f32 v[18:19], v[6:7], v[54:55], v[18:19]
	v_pk_mul_f32 v[20:21], v[64:65], v[72:73] op_sel_hi:[1,0]
	v_pk_mul_f32 v[22:23], v[66:67], v[72:73] op_sel_hi:[1,0]
	v_add_f32_e32 v32, v16, v17
	v_add_f32_e32 v33, v18, v19
	v_pk_mul_f32 v[24:25], v[64:65], v[72:73] op_sel:[0,1] op_sel_hi:[1,1]
	v_pk_mul_f32 v[26:27], v[66:67], v[72:73] op_sel:[0,1] op_sel_hi:[1,1]
	v_cndmask_b32_e64 v34, v32, v33, s[6:7]
	v_cndmask_b32_e64 v35, v33, v32, s[6:7]
	v_pk_mul_f32 v[38:39], v[72:73], v[124:125] op_sel:[0,1] op_sel_hi:[1,1]
	v_pk_fma_f32 v[20:21], v[60:61], v[8:9], v[20:21] op_sel_hi:[1,0,1]
	v_add_f32_dpp v35, v34, v35 row_ror:8 row_mask:0xf bank_mask:0xf bound_ctrl:1
	v_pk_fma_f32 v[22:23], v[62:63], v[8:9], v[22:23] op_sel_hi:[1,0,1]
	v_pk_fma_f32 v[24:25], v[60:61], v[8:9], v[24:25] op_sel:[0,1,0] op_sel_hi:[1,1,1]
	v_pk_fma_f32 v[26:27], v[62:63], v[8:9], v[26:27] op_sel:[0,1,0] op_sel_hi:[1,1,1]
	v_add_f32_dpp v35, v35, v35 quad_perm:[1,0,3,2] row_mask:0xf bank_mask:0xf bound_ctrl:1
	v_pk_fma_f32 v[0:1], v[0:1], v[56:57], v[20:21]
	v_pk_fma_f32 v[2:3], v[2:3], v[58:59], v[22:23]
	v_pk_fma_f32 v[4:5], v[4:5], v[56:57], v[24:25]
	v_add_f32_dpp v35, v35, v35 quad_perm:[2,3,0,1] row_mask:0xf bank_mask:0xf bound_ctrl:1
	v_pk_fma_f32 v[6:7], v[6:7], v[58:59], v[26:27]
	v_pk_mul_f32 v[28:29], v[0:1], v[68:69]
	v_pk_fma_f32 v[38:39], v[8:9], v[124:125], v[38:39] op_sel_hi:[1,0,1]
	v_add_f32_dpp v35, v35, v35 row_half_mirror row_mask:0xf bank_mask:0xf bound_ctrl:1
	v_pk_mul_f32 v[30:31], v[4:5], v[68:69]
	v_pk_fma_f32 v[28:29], v[2:3], v[70:71], v[28:29]
	v_pk_fma_f32 v[30:31], v[6:7], v[70:71], v[30:31]
	v_mov_b32_dpp v34, v35 row_ror:8 row_mask:0xf bank_mask:0xf
	v_add_f32_e32 v16, v28, v29
	v_add_f32_e32 v17, v30, v31
	v_cndmask_b32_e64 v32, v34, v35, s[6:7]
	v_cndmask_b32_e64 v33, v35, v34, s[6:7]
	v_cndmask_b32_e64 v18, v16, v17, s[6:7]
	v_cndmask_b32_e64 v19, v17, v16, s[6:7]
	v_pk_add_f32 v[8:9], v[32:33], v[38:39] neg_lo:[1,1] neg_hi:[1,1]
	s_nop 0
	v_add_f32_dpp v36, v18, v19 row_ror:8 row_mask:0xf bank_mask:0xf bound_ctrl:1
	ds_write_b32 v13, v36 offset:0
	s_waitcnt lgkmcnt(8)
	ds_read_b128 v[52:55], v10 offset:768
	ds_read_b64 v[72:73], v11 offset:768
	ds_read_b128 v[64:67], v10 offset:13056
	ds_read_b128 v[60:63], v10 offset:8960
	ds_read_b128 v[56:59], v10 offset:4864
	ds_read_b128 v[68:71], v10 offset:17152
	v_pk_mul_f32 v[16:17], v[0:1], v[76:77]
	v_pk_mul_f32 v[18:19], v[4:5], v[76:77]
	v_pk_fma_f32 v[16:17], v[2:3], v[78:79], v[16:17]
	v_pk_fma_f32 v[18:19], v[6:7], v[78:79], v[18:19]
	v_pk_mul_f32 v[20:21], v[88:89], v[96:97] op_sel_hi:[1,0]
	v_pk_mul_f32 v[22:23], v[90:91], v[96:97] op_sel_hi:[1,0]
	v_add_f32_e32 v32, v16, v17
	v_add_f32_e32 v33, v18, v19
	v_pk_mul_f32 v[24:25], v[88:89], v[96:97] op_sel:[0,1] op_sel_hi:[1,1]
	v_pk_mul_f32 v[26:27], v[90:91], v[96:97] op_sel:[0,1] op_sel_hi:[1,1]
	v_cndmask_b32_e64 v34, v32, v33, s[6:7]
	v_cndmask_b32_e64 v35, v33, v32, s[6:7]
	v_pk_mul_f32 v[38:39], v[96:97], v[126:127] op_sel:[0,1] op_sel_hi:[1,1]
	v_pk_fma_f32 v[20:21], v[84:85], v[8:9], v[20:21] op_sel_hi:[1,0,1]
	v_add_f32_dpp v35, v34, v35 row_ror:8 row_mask:0xf bank_mask:0xf bound_ctrl:1
	v_pk_fma_f32 v[22:23], v[86:87], v[8:9], v[22:23] op_sel_hi:[1,0,1]
	v_pk_fma_f32 v[24:25], v[84:85], v[8:9], v[24:25] op_sel:[0,1,0] op_sel_hi:[1,1,1]
	v_pk_fma_f32 v[26:27], v[86:87], v[8:9], v[26:27] op_sel:[0,1,0] op_sel_hi:[1,1,1]
	v_add_f32_dpp v35, v35, v35 quad_perm:[1,0,3,2] row_mask:0xf bank_mask:0xf bound_ctrl:1
	v_pk_fma_f32 v[0:1], v[0:1], v[80:81], v[20:21]
	v_pk_fma_f32 v[2:3], v[2:3], v[82:83], v[22:23]
	v_pk_fma_f32 v[4:5], v[4:5], v[80:81], v[24:25]
	v_add_f32_dpp v35, v35, v35 quad_perm:[2,3,0,1] row_mask:0xf bank_mask:0xf bound_ctrl:1
	v_pk_fma_f32 v[6:7], v[6:7], v[82:83], v[26:27]
	v_pk_mul_f32 v[28:29], v[0:1], v[92:93]
	v_pk_fma_f32 v[38:39], v[8:9], v[126:127], v[38:39] op_sel_hi:[1,0,1]
	v_add_f32_dpp v35, v35, v35 row_half_mirror row_mask:0xf bank_mask:0xf bound_ctrl:1
	v_pk_mul_f32 v[30:31], v[4:5], v[92:93]
	v_pk_fma_f32 v[28:29], v[2:3], v[94:95], v[28:29]
	v_pk_fma_f32 v[30:31], v[6:7], v[94:95], v[30:31]
	v_mov_b32_dpp v34, v35 row_ror:8 row_mask:0xf bank_mask:0xf
	v_add_f32_e32 v16, v28, v29
	v_add_f32_e32 v17, v30, v31
	v_cndmask_b32_e64 v32, v34, v35, s[6:7]
	v_cndmask_b32_e64 v33, v35, v34, s[6:7]
	v_cndmask_b32_e64 v18, v16, v17, s[6:7]
	v_cndmask_b32_e64 v19, v17, v16, s[6:7]
	v_pk_add_f32 v[8:9], v[32:33], v[38:39] neg_lo:[1,1] neg_hi:[1,1]
	s_nop 0
	v_add_f32_dpp v36, v18, v19 row_ror:8 row_mask:0xf bank_mask:0xf bound_ctrl:1
	ds_write_b32 v13, v36 offset:256
	s_waitcnt lgkmcnt(8)
	ds_read_b128 v[76:79], v10 offset:1024
	ds_read_b64 v[96:97], v11 offset:1024
	ds_read_b128 v[88:91], v10 offset:13312
	ds_read_b128 v[84:87], v10 offset:9216
	ds_read_b128 v[80:83], v10 offset:5120
	ds_read_b128 v[92:95], v10 offset:17408
	ds_read_b128 v[124:127], v12 offset:32
	v_pk_mul_f32 v[16:17], v[0:1], v[100:101]
	v_pk_mul_f32 v[18:19], v[4:5], v[100:101]
	v_pk_fma_f32 v[16:17], v[2:3], v[102:103], v[16:17]
	v_pk_fma_f32 v[18:19], v[6:7], v[102:103], v[18:19]
	v_pk_mul_f32 v[20:21], v[112:113], v[120:121] op_sel_hi:[1,0]
	v_pk_mul_f32 v[22:23], v[114:115], v[120:121] op_sel_hi:[1,0]
	v_add_f32_e32 v32, v16, v17
	v_add_f32_e32 v33, v18, v19
	v_pk_mul_f32 v[24:25], v[112:113], v[120:121] op_sel:[0,1] op_sel_hi:[1,1]
	v_pk_mul_f32 v[26:27], v[114:115], v[120:121] op_sel:[0,1] op_sel_hi:[1,1]
	v_cndmask_b32_e64 v34, v32, v33, s[6:7]
	v_cndmask_b32_e64 v35, v33, v32, s[6:7]
	v_pk_mul_f32 v[38:39], v[120:121], v[128:129] op_sel:[0,1] op_sel_hi:[1,1]
	v_pk_fma_f32 v[20:21], v[108:109], v[8:9], v[20:21] op_sel_hi:[1,0,1]
	v_add_f32_dpp v35, v34, v35 row_ror:8 row_mask:0xf bank_mask:0xf bound_ctrl:1
	v_pk_fma_f32 v[22:23], v[110:111], v[8:9], v[22:23] op_sel_hi:[1,0,1]
	v_pk_fma_f32 v[24:25], v[108:109], v[8:9], v[24:25] op_sel:[0,1,0] op_sel_hi:[1,1,1]
	v_pk_fma_f32 v[26:27], v[110:111], v[8:9], v[26:27] op_sel:[0,1,0] op_sel_hi:[1,1,1]
	v_add_f32_dpp v35, v35, v35 quad_perm:[1,0,3,2] row_mask:0xf bank_mask:0xf bound_ctrl:1
	v_pk_fma_f32 v[0:1], v[0:1], v[104:105], v[20:21]
	v_pk_fma_f32 v[2:3], v[2:3], v[106:107], v[22:23]
	v_pk_fma_f32 v[4:5], v[4:5], v[104:105], v[24:25]
	v_add_f32_dpp v35, v35, v35 quad_perm:[2,3,0,1] row_mask:0xf bank_mask:0xf bound_ctrl:1
	v_pk_fma_f32 v[6:7], v[6:7], v[106:107], v[26:27]
	v_pk_mul_f32 v[28:29], v[0:1], v[116:117]
	v_pk_fma_f32 v[38:39], v[8:9], v[128:129], v[38:39] op_sel_hi:[1,0,1]
	v_add_f32_dpp v35, v35, v35 row_half_mirror row_mask:0xf bank_mask:0xf bound_ctrl:1
	v_pk_mul_f32 v[30:31], v[4:5], v[116:117]
	v_pk_fma_f32 v[28:29], v[2:3], v[118:119], v[28:29]
	v_pk_fma_f32 v[30:31], v[6:7], v[118:119], v[30:31]
	v_mov_b32_dpp v34, v35 row_ror:8 row_mask:0xf bank_mask:0xf
	v_add_f32_e32 v16, v28, v29
	v_add_f32_e32 v17, v30, v31
	v_cndmask_b32_e64 v32, v34, v35, s[6:7]
	v_cndmask_b32_e64 v33, v35, v34, s[6:7]
	v_cndmask_b32_e64 v18, v16, v17, s[6:7]
	v_cndmask_b32_e64 v19, v17, v16, s[6:7]
	v_pk_add_f32 v[8:9], v[32:33], v[38:39] neg_lo:[1,1] neg_hi:[1,1]
	s_nop 0
	v_add_f32_dpp v36, v18, v19 row_ror:8 row_mask:0xf bank_mask:0xf bound_ctrl:1
	ds_write_b32 v13, v36 offset:512
	s_waitcnt lgkmcnt(9)
	ds_read_b128 v[100:103], v10 offset:1280
	ds_read_b64 v[120:121], v11 offset:1280
	ds_read_b128 v[112:115], v10 offset:13568
	ds_read_b128 v[108:111], v10 offset:9472
	ds_read_b128 v[104:107], v10 offset:5376
	ds_read_b128 v[116:119], v10 offset:17664
	v_pk_mul_f32 v[16:17], v[0:1], v[52:53]
	v_pk_mul_f32 v[18:19], v[4:5], v[52:53]
	v_pk_fma_f32 v[16:17], v[2:3], v[54:55], v[16:17]
	v_pk_fma_f32 v[18:19], v[6:7], v[54:55], v[18:19]
	v_pk_mul_f32 v[20:21], v[64:65], v[72:73] op_sel_hi:[1,0]
	v_pk_mul_f32 v[22:23], v[66:67], v[72:73] op_sel_hi:[1,0]
	v_add_f32_e32 v32, v16, v17
	v_add_f32_e32 v33, v18, v19
	v_pk_mul_f32 v[24:25], v[64:65], v[72:73] op_sel:[0,1] op_sel_hi:[1,1]
	v_pk_mul_f32 v[26:27], v[66:67], v[72:73] op_sel:[0,1] op_sel_hi:[1,1]
	v_cndmask_b32_e64 v34, v32, v33, s[6:7]
	v_cndmask_b32_e64 v35, v33, v32, s[6:7]
	v_pk_mul_f32 v[38:39], v[72:73], v[130:131] op_sel:[0,1] op_sel_hi:[1,1]
	v_pk_fma_f32 v[20:21], v[60:61], v[8:9], v[20:21] op_sel_hi:[1,0,1]
	v_add_f32_dpp v35, v34, v35 row_ror:8 row_mask:0xf bank_mask:0xf bound_ctrl:1
	v_pk_fma_f32 v[22:23], v[62:63], v[8:9], v[22:23] op_sel_hi:[1,0,1]
	v_pk_fma_f32 v[24:25], v[60:61], v[8:9], v[24:25] op_sel:[0,1,0] op_sel_hi:[1,1,1]
	v_pk_fma_f32 v[26:27], v[62:63], v[8:9], v[26:27] op_sel:[0,1,0] op_sel_hi:[1,1,1]
	v_add_f32_dpp v35, v35, v35 quad_perm:[1,0,3,2] row_mask:0xf bank_mask:0xf bound_ctrl:1
	v_pk_fma_f32 v[0:1], v[0:1], v[56:57], v[20:21]
	v_pk_fma_f32 v[2:3], v[2:3], v[58:59], v[22:23]
	v_pk_fma_f32 v[4:5], v[4:5], v[56:57], v[24:25]
	v_add_f32_dpp v35, v35, v35 quad_perm:[2,3,0,1] row_mask:0xf bank_mask:0xf bound_ctrl:1
	v_pk_fma_f32 v[6:7], v[6:7], v[58:59], v[26:27]
	v_pk_mul_f32 v[28:29], v[0:1], v[68:69]
	v_pk_fma_f32 v[38:39], v[8:9], v[130:131], v[38:39] op_sel_hi:[1,0,1]
	v_add_f32_dpp v35, v35, v35 row_half_mirror row_mask:0xf bank_mask:0xf bound_ctrl:1
	v_pk_mul_f32 v[30:31], v[4:5], v[68:69]
	v_pk_fma_f32 v[28:29], v[2:3], v[70:71], v[28:29]
	v_pk_fma_f32 v[30:31], v[6:7], v[70:71], v[30:31]
	v_mov_b32_dpp v34, v35 row_ror:8 row_mask:0xf bank_mask:0xf
	v_add_f32_e32 v16, v28, v29
	v_add_f32_e32 v17, v30, v31
	v_cndmask_b32_e64 v32, v34, v35, s[6:7]
	v_cndmask_b32_e64 v33, v35, v34, s[6:7]
	v_cndmask_b32_e64 v18, v16, v17, s[6:7]
	v_cndmask_b32_e64 v19, v17, v16, s[6:7]
	v_pk_add_f32 v[8:9], v[32:33], v[38:39] neg_lo:[1,1] neg_hi:[1,1]
	s_nop 0
	v_add_f32_dpp v36, v18, v19 row_ror:8 row_mask:0xf bank_mask:0xf bound_ctrl:1
	ds_write_b32 v13, v36 offset:768
	s_waitcnt lgkmcnt(8)
	ds_read_b128 v[52:55], v10 offset:1536
	ds_read_b64 v[72:73], v11 offset:1536
	ds_read_b128 v[64:67], v10 offset:13824
	ds_read_b128 v[60:63], v10 offset:9728
	ds_read_b128 v[56:59], v10 offset:5632
	ds_read_b128 v[68:71], v10 offset:17920
	ds_read_b128 v[128:131], v12 offset:48
	v_pk_mul_f32 v[16:17], v[0:1], v[76:77]
	v_pk_mul_f32 v[18:19], v[4:5], v[76:77]
	v_pk_fma_f32 v[16:17], v[2:3], v[78:79], v[16:17]
	v_pk_fma_f32 v[18:19], v[6:7], v[78:79], v[18:19]
	v_pk_mul_f32 v[20:21], v[88:89], v[96:97] op_sel_hi:[1,0]
	v_pk_mul_f32 v[22:23], v[90:91], v[96:97] op_sel_hi:[1,0]
	v_add_f32_e32 v32, v16, v17
	v_add_f32_e32 v33, v18, v19
	v_pk_mul_f32 v[24:25], v[88:89], v[96:97] op_sel:[0,1] op_sel_hi:[1,1]
	v_pk_mul_f32 v[26:27], v[90:91], v[96:97] op_sel:[0,1] op_sel_hi:[1,1]
	v_cndmask_b32_e64 v34, v32, v33, s[6:7]
	v_cndmask_b32_e64 v35, v33, v32, s[6:7]
	v_pk_mul_f32 v[38:39], v[96:97], v[124:125] op_sel:[0,1] op_sel_hi:[1,1]
	v_pk_fma_f32 v[20:21], v[84:85], v[8:9], v[20:21] op_sel_hi:[1,0,1]
	v_add_f32_dpp v35, v34, v35 row_ror:8 row_mask:0xf bank_mask:0xf bound_ctrl:1
	v_pk_fma_f32 v[22:23], v[86:87], v[8:9], v[22:23] op_sel_hi:[1,0,1]
	v_pk_fma_f32 v[24:25], v[84:85], v[8:9], v[24:25] op_sel:[0,1,0] op_sel_hi:[1,1,1]
	v_pk_fma_f32 v[26:27], v[86:87], v[8:9], v[26:27] op_sel:[0,1,0] op_sel_hi:[1,1,1]
	v_add_f32_dpp v35, v35, v35 quad_perm:[1,0,3,2] row_mask:0xf bank_mask:0xf bound_ctrl:1
	v_pk_fma_f32 v[0:1], v[0:1], v[80:81], v[20:21]
	v_pk_fma_f32 v[2:3], v[2:3], v[82:83], v[22:23]
	v_pk_fma_f32 v[4:5], v[4:5], v[80:81], v[24:25]
	v_add_f32_dpp v35, v35, v35 quad_perm:[2,3,0,1] row_mask:0xf bank_mask:0xf bound_ctrl:1
	v_pk_fma_f32 v[6:7], v[6:7], v[82:83], v[26:27]
	v_pk_mul_f32 v[28:29], v[0:1], v[92:93]
	v_pk_fma_f32 v[38:39], v[8:9], v[124:125], v[38:39] op_sel_hi:[1,0,1]
	v_add_f32_dpp v35, v35, v35 row_half_mirror row_mask:0xf bank_mask:0xf bound_ctrl:1
	v_pk_mul_f32 v[30:31], v[4:5], v[92:93]
	v_pk_fma_f32 v[28:29], v[2:3], v[94:95], v[28:29]
	v_pk_fma_f32 v[30:31], v[6:7], v[94:95], v[30:31]
	v_mov_b32_dpp v34, v35 row_ror:8 row_mask:0xf bank_mask:0xf
	v_add_f32_e32 v16, v28, v29
	v_add_f32_e32 v17, v30, v31
	v_cndmask_b32_e64 v32, v34, v35, s[6:7]
	v_cndmask_b32_e64 v33, v35, v34, s[6:7]
	v_cndmask_b32_e64 v18, v16, v17, s[6:7]
	v_cndmask_b32_e64 v19, v17, v16, s[6:7]
	v_pk_add_f32 v[8:9], v[32:33], v[38:39] neg_lo:[1,1] neg_hi:[1,1]
	s_nop 0
	v_add_f32_dpp v36, v18, v19 row_ror:8 row_mask:0xf bank_mask:0xf bound_ctrl:1
	ds_write_b32 v13, v36 offset:1024
	s_waitcnt lgkmcnt(9)
	ds_read_b128 v[76:79], v10 offset:1792
	ds_read_b64 v[96:97], v11 offset:1792
	ds_read_b128 v[88:91], v10 offset:14080
	ds_read_b128 v[84:87], v10 offset:9984
	ds_read_b128 v[80:83], v10 offset:5888
	ds_read_b128 v[92:95], v10 offset:18176
	v_pk_mul_f32 v[16:17], v[0:1], v[100:101]
	v_pk_mul_f32 v[18:19], v[4:5], v[100:101]
	v_pk_fma_f32 v[16:17], v[2:3], v[102:103], v[16:17]
	v_pk_fma_f32 v[18:19], v[6:7], v[102:103], v[18:19]
	v_pk_mul_f32 v[20:21], v[112:113], v[120:121] op_sel_hi:[1,0]
	v_pk_mul_f32 v[22:23], v[114:115], v[120:121] op_sel_hi:[1,0]
	v_add_f32_e32 v32, v16, v17
	v_add_f32_e32 v33, v18, v19
	v_pk_mul_f32 v[24:25], v[112:113], v[120:121] op_sel:[0,1] op_sel_hi:[1,1]
	v_pk_mul_f32 v[26:27], v[114:115], v[120:121] op_sel:[0,1] op_sel_hi:[1,1]
	v_cndmask_b32_e64 v34, v32, v33, s[6:7]
	v_cndmask_b32_e64 v35, v33, v32, s[6:7]
	v_pk_mul_f32 v[38:39], v[120:121], v[126:127] op_sel:[0,1] op_sel_hi:[1,1]
	v_pk_fma_f32 v[20:21], v[108:109], v[8:9], v[20:21] op_sel_hi:[1,0,1]
	v_add_f32_dpp v35, v34, v35 row_ror:8 row_mask:0xf bank_mask:0xf bound_ctrl:1
	v_pk_fma_f32 v[22:23], v[110:111], v[8:9], v[22:23] op_sel_hi:[1,0,1]
	v_pk_fma_f32 v[24:25], v[108:109], v[8:9], v[24:25] op_sel:[0,1,0] op_sel_hi:[1,1,1]
	v_pk_fma_f32 v[26:27], v[110:111], v[8:9], v[26:27] op_sel:[0,1,0] op_sel_hi:[1,1,1]
	v_add_f32_dpp v35, v35, v35 quad_perm:[1,0,3,2] row_mask:0xf bank_mask:0xf bound_ctrl:1
	v_pk_fma_f32 v[0:1], v[0:1], v[104:105], v[20:21]
	v_pk_fma_f32 v[2:3], v[2:3], v[106:107], v[22:23]
	v_pk_fma_f32 v[4:5], v[4:5], v[104:105], v[24:25]
	v_add_f32_dpp v35, v35, v35 quad_perm:[2,3,0,1] row_mask:0xf bank_mask:0xf bound_ctrl:1
	v_pk_fma_f32 v[6:7], v[6:7], v[106:107], v[26:27]
	v_pk_mul_f32 v[28:29], v[0:1], v[116:117]
	v_pk_fma_f32 v[38:39], v[8:9], v[126:127], v[38:39] op_sel_hi:[1,0,1]
	v_add_f32_dpp v35, v35, v35 row_half_mirror row_mask:0xf bank_mask:0xf bound_ctrl:1
	v_pk_mul_f32 v[30:31], v[4:5], v[116:117]
	v_pk_fma_f32 v[28:29], v[2:3], v[118:119], v[28:29]
	v_pk_fma_f32 v[30:31], v[6:7], v[118:119], v[30:31]
	v_mov_b32_dpp v34, v35 row_ror:8 row_mask:0xf bank_mask:0xf
	v_add_f32_e32 v16, v28, v29
	v_add_f32_e32 v17, v30, v31
	v_cndmask_b32_e64 v32, v34, v35, s[6:7]
	v_cndmask_b32_e64 v33, v35, v34, s[6:7]
	v_cndmask_b32_e64 v18, v16, v17, s[6:7]
	v_cndmask_b32_e64 v19, v17, v16, s[6:7]
	v_pk_add_f32 v[8:9], v[32:33], v[38:39] neg_lo:[1,1] neg_hi:[1,1]
	s_nop 0
	v_add_f32_dpp v36, v18, v19 row_ror:8 row_mask:0xf bank_mask:0xf bound_ctrl:1
	ds_write_b32 v13, v36 offset:1280
	s_waitcnt lgkmcnt(8)
	ds_read_b128 v[100:103], v10 offset:2048
	ds_read_b64 v[120:121], v11 offset:2048
	ds_read_b128 v[112:115], v10 offset:14336
	ds_read_b128 v[108:111], v10 offset:10240
	ds_read_b128 v[104:107], v10 offset:6144
	ds_read_b128 v[116:119], v10 offset:18432
	ds_read_b128 v[124:127], v12 offset:64
	v_pk_mul_f32 v[16:17], v[0:1], v[52:53]
	v_pk_mul_f32 v[18:19], v[4:5], v[52:53]
	v_pk_fma_f32 v[16:17], v[2:3], v[54:55], v[16:17]
	v_pk_fma_f32 v[18:19], v[6:7], v[54:55], v[18:19]
	v_pk_mul_f32 v[20:21], v[64:65], v[72:73] op_sel_hi:[1,0]
	v_pk_mul_f32 v[22:23], v[66:67], v[72:73] op_sel_hi:[1,0]
	v_add_f32_e32 v32, v16, v17
	v_add_f32_e32 v33, v18, v19
	v_pk_mul_f32 v[24:25], v[64:65], v[72:73] op_sel:[0,1] op_sel_hi:[1,1]
	v_pk_mul_f32 v[26:27], v[66:67], v[72:73] op_sel:[0,1] op_sel_hi:[1,1]
	v_cndmask_b32_e64 v34, v32, v33, s[6:7]
	v_cndmask_b32_e64 v35, v33, v32, s[6:7]
	v_pk_mul_f32 v[38:39], v[72:73], v[128:129] op_sel:[0,1] op_sel_hi:[1,1]
	v_pk_fma_f32 v[20:21], v[60:61], v[8:9], v[20:21] op_sel_hi:[1,0,1]
	v_add_f32_dpp v35, v34, v35 row_ror:8 row_mask:0xf bank_mask:0xf bound_ctrl:1
	v_pk_fma_f32 v[22:23], v[62:63], v[8:9], v[22:23] op_sel_hi:[1,0,1]
	v_pk_fma_f32 v[24:25], v[60:61], v[8:9], v[24:25] op_sel:[0,1,0] op_sel_hi:[1,1,1]
	v_pk_fma_f32 v[26:27], v[62:63], v[8:9], v[26:27] op_sel:[0,1,0] op_sel_hi:[1,1,1]
	v_add_f32_dpp v35, v35, v35 quad_perm:[1,0,3,2] row_mask:0xf bank_mask:0xf bound_ctrl:1
	v_pk_fma_f32 v[0:1], v[0:1], v[56:57], v[20:21]
	v_pk_fma_f32 v[2:3], v[2:3], v[58:59], v[22:23]
	v_pk_fma_f32 v[4:5], v[4:5], v[56:57], v[24:25]
	v_add_f32_dpp v35, v35, v35 quad_perm:[2,3,0,1] row_mask:0xf bank_mask:0xf bound_ctrl:1
	v_pk_fma_f32 v[6:7], v[6:7], v[58:59], v[26:27]
	v_pk_mul_f32 v[28:29], v[0:1], v[68:69]
	v_pk_fma_f32 v[38:39], v[8:9], v[128:129], v[38:39] op_sel_hi:[1,0,1]
	v_add_f32_dpp v35, v35, v35 row_half_mirror row_mask:0xf bank_mask:0xf bound_ctrl:1
	v_pk_mul_f32 v[30:31], v[4:5], v[68:69]
	v_pk_fma_f32 v[28:29], v[2:3], v[70:71], v[28:29]
	v_pk_fma_f32 v[30:31], v[6:7], v[70:71], v[30:31]
	v_mov_b32_dpp v34, v35 row_ror:8 row_mask:0xf bank_mask:0xf
	v_add_f32_e32 v16, v28, v29
	v_add_f32_e32 v17, v30, v31
	v_cndmask_b32_e64 v32, v34, v35, s[6:7]
	v_cndmask_b32_e64 v33, v35, v34, s[6:7]
	v_cndmask_b32_e64 v18, v16, v17, s[6:7]
	v_cndmask_b32_e64 v19, v17, v16, s[6:7]
	v_pk_add_f32 v[8:9], v[32:33], v[38:39] neg_lo:[1,1] neg_hi:[1,1]
	s_nop 0
	v_add_f32_dpp v36, v18, v19 row_ror:8 row_mask:0xf bank_mask:0xf bound_ctrl:1
	ds_write_b32 v13, v36 offset:1536
	s_waitcnt lgkmcnt(9)
	ds_read_b128 v[52:55], v10 offset:2304
	ds_read_b64 v[72:73], v11 offset:2304
	ds_read_b128 v[64:67], v10 offset:14592
	ds_read_b128 v[60:63], v10 offset:10496
	ds_read_b128 v[56:59], v10 offset:6400
	ds_read_b128 v[68:71], v10 offset:18688
	v_pk_mul_f32 v[16:17], v[0:1], v[76:77]
	v_pk_mul_f32 v[18:19], v[4:5], v[76:77]
	v_pk_fma_f32 v[16:17], v[2:3], v[78:79], v[16:17]
	v_pk_fma_f32 v[18:19], v[6:7], v[78:79], v[18:19]
	v_pk_mul_f32 v[20:21], v[88:89], v[96:97] op_sel_hi:[1,0]
	v_pk_mul_f32 v[22:23], v[90:91], v[96:97] op_sel_hi:[1,0]
	v_add_f32_e32 v32, v16, v17
	v_add_f32_e32 v33, v18, v19
	v_pk_mul_f32 v[24:25], v[88:89], v[96:97] op_sel:[0,1] op_sel_hi:[1,1]
	v_pk_mul_f32 v[26:27], v[90:91], v[96:97] op_sel:[0,1] op_sel_hi:[1,1]
	v_cndmask_b32_e64 v34, v32, v33, s[6:7]
	v_cndmask_b32_e64 v35, v33, v32, s[6:7]
	v_pk_mul_f32 v[38:39], v[96:97], v[130:131] op_sel:[0,1] op_sel_hi:[1,1]
	v_pk_fma_f32 v[20:21], v[84:85], v[8:9], v[20:21] op_sel_hi:[1,0,1]
	v_add_f32_dpp v35, v34, v35 row_ror:8 row_mask:0xf bank_mask:0xf bound_ctrl:1
	v_pk_fma_f32 v[22:23], v[86:87], v[8:9], v[22:23] op_sel_hi:[1,0,1]
	v_pk_fma_f32 v[24:25], v[84:85], v[8:9], v[24:25] op_sel:[0,1,0] op_sel_hi:[1,1,1]
	v_pk_fma_f32 v[26:27], v[86:87], v[8:9], v[26:27] op_sel:[0,1,0] op_sel_hi:[1,1,1]
	v_add_f32_dpp v35, v35, v35 quad_perm:[1,0,3,2] row_mask:0xf bank_mask:0xf bound_ctrl:1
	v_pk_fma_f32 v[0:1], v[0:1], v[80:81], v[20:21]
	v_pk_fma_f32 v[2:3], v[2:3], v[82:83], v[22:23]
	v_pk_fma_f32 v[4:5], v[4:5], v[80:81], v[24:25]
	v_add_f32_dpp v35, v35, v35 quad_perm:[2,3,0,1] row_mask:0xf bank_mask:0xf bound_ctrl:1
	v_pk_fma_f32 v[6:7], v[6:7], v[82:83], v[26:27]
	v_pk_mul_f32 v[28:29], v[0:1], v[92:93]
	v_pk_fma_f32 v[38:39], v[8:9], v[130:131], v[38:39] op_sel_hi:[1,0,1]
	v_add_f32_dpp v35, v35, v35 row_half_mirror row_mask:0xf bank_mask:0xf bound_ctrl:1
	v_pk_mul_f32 v[30:31], v[4:5], v[92:93]
	v_pk_fma_f32 v[28:29], v[2:3], v[94:95], v[28:29]
	v_pk_fma_f32 v[30:31], v[6:7], v[94:95], v[30:31]
	v_mov_b32_dpp v34, v35 row_ror:8 row_mask:0xf bank_mask:0xf
	v_add_f32_e32 v16, v28, v29
	v_add_f32_e32 v17, v30, v31
	v_cndmask_b32_e64 v32, v34, v35, s[6:7]
	v_cndmask_b32_e64 v33, v35, v34, s[6:7]
	v_cndmask_b32_e64 v18, v16, v17, s[6:7]
	v_cndmask_b32_e64 v19, v17, v16, s[6:7]
	v_pk_add_f32 v[8:9], v[32:33], v[38:39] neg_lo:[1,1] neg_hi:[1,1]
	s_nop 0
	v_add_f32_dpp v36, v18, v19 row_ror:8 row_mask:0xf bank_mask:0xf bound_ctrl:1
	ds_write_b32 v13, v36 offset:1792
	s_waitcnt lgkmcnt(8)
	ds_read_b128 v[76:79], v10 offset:2560
	ds_read_b64 v[96:97], v11 offset:2560
	ds_read_b128 v[88:91], v10 offset:14848
	ds_read_b128 v[84:87], v10 offset:10752
	ds_read_b128 v[80:83], v10 offset:6656
	ds_read_b128 v[92:95], v10 offset:18944
	ds_read_b128 v[128:131], v12 offset:80
	v_pk_mul_f32 v[16:17], v[0:1], v[100:101]
	v_pk_mul_f32 v[18:19], v[4:5], v[100:101]
	v_pk_fma_f32 v[16:17], v[2:3], v[102:103], v[16:17]
	v_pk_fma_f32 v[18:19], v[6:7], v[102:103], v[18:19]
	v_pk_mul_f32 v[20:21], v[112:113], v[120:121] op_sel_hi:[1,0]
	v_pk_mul_f32 v[22:23], v[114:115], v[120:121] op_sel_hi:[1,0]
	v_add_f32_e32 v32, v16, v17
	v_add_f32_e32 v33, v18, v19
	v_pk_mul_f32 v[24:25], v[112:113], v[120:121] op_sel:[0,1] op_sel_hi:[1,1]
	v_pk_mul_f32 v[26:27], v[114:115], v[120:121] op_sel:[0,1] op_sel_hi:[1,1]
	v_cndmask_b32_e64 v34, v32, v33, s[6:7]
	v_cndmask_b32_e64 v35, v33, v32, s[6:7]
	v_pk_mul_f32 v[38:39], v[120:121], v[124:125] op_sel:[0,1] op_sel_hi:[1,1]
	v_pk_fma_f32 v[20:21], v[108:109], v[8:9], v[20:21] op_sel_hi:[1,0,1]
	v_add_f32_dpp v35, v34, v35 row_ror:8 row_mask:0xf bank_mask:0xf bound_ctrl:1
	v_pk_fma_f32 v[22:23], v[110:111], v[8:9], v[22:23] op_sel_hi:[1,0,1]
	v_pk_fma_f32 v[24:25], v[108:109], v[8:9], v[24:25] op_sel:[0,1,0] op_sel_hi:[1,1,1]
	v_pk_fma_f32 v[26:27], v[110:111], v[8:9], v[26:27] op_sel:[0,1,0] op_sel_hi:[1,1,1]
	v_add_f32_dpp v35, v35, v35 quad_perm:[1,0,3,2] row_mask:0xf bank_mask:0xf bound_ctrl:1
	v_pk_fma_f32 v[0:1], v[0:1], v[104:105], v[20:21]
	v_pk_fma_f32 v[2:3], v[2:3], v[106:107], v[22:23]
	v_pk_fma_f32 v[4:5], v[4:5], v[104:105], v[24:25]
	v_add_f32_dpp v35, v35, v35 quad_perm:[2,3,0,1] row_mask:0xf bank_mask:0xf bound_ctrl:1
	v_pk_fma_f32 v[6:7], v[6:7], v[106:107], v[26:27]
	v_pk_mul_f32 v[28:29], v[0:1], v[116:117]
	v_pk_fma_f32 v[38:39], v[8:9], v[124:125], v[38:39] op_sel_hi:[1,0,1]
	v_add_f32_dpp v35, v35, v35 row_half_mirror row_mask:0xf bank_mask:0xf bound_ctrl:1
	v_pk_mul_f32 v[30:31], v[4:5], v[116:117]
	v_pk_fma_f32 v[28:29], v[2:3], v[118:119], v[28:29]
	v_pk_fma_f32 v[30:31], v[6:7], v[118:119], v[30:31]
	v_mov_b32_dpp v34, v35 row_ror:8 row_mask:0xf bank_mask:0xf
	v_add_f32_e32 v16, v28, v29
	v_add_f32_e32 v17, v30, v31
	v_cndmask_b32_e64 v32, v34, v35, s[6:7]
	v_cndmask_b32_e64 v33, v35, v34, s[6:7]
	v_cndmask_b32_e64 v18, v16, v17, s[6:7]
	v_cndmask_b32_e64 v19, v17, v16, s[6:7]
	v_pk_add_f32 v[8:9], v[32:33], v[38:39] neg_lo:[1,1] neg_hi:[1,1]
	s_nop 0
	v_add_f32_dpp v36, v18, v19 row_ror:8 row_mask:0xf bank_mask:0xf bound_ctrl:1
	ds_write_b32 v13, v36 offset:2048
	s_waitcnt lgkmcnt(9)
	ds_read_b128 v[100:103], v10 offset:2816
	ds_read_b64 v[120:121], v11 offset:2816
	ds_read_b128 v[112:115], v10 offset:15104
	ds_read_b128 v[108:111], v10 offset:11008
	ds_read_b128 v[104:107], v10 offset:6912
	ds_read_b128 v[116:119], v10 offset:19200
	v_pk_mul_f32 v[16:17], v[0:1], v[52:53]
	v_pk_mul_f32 v[18:19], v[4:5], v[52:53]
	v_pk_fma_f32 v[16:17], v[2:3], v[54:55], v[16:17]
	v_pk_fma_f32 v[18:19], v[6:7], v[54:55], v[18:19]
	v_pk_mul_f32 v[20:21], v[64:65], v[72:73] op_sel_hi:[1,0]
	v_pk_mul_f32 v[22:23], v[66:67], v[72:73] op_sel_hi:[1,0]
	v_add_f32_e32 v32, v16, v17
	v_add_f32_e32 v33, v18, v19
	v_pk_mul_f32 v[24:25], v[64:65], v[72:73] op_sel:[0,1] op_sel_hi:[1,1]
	v_pk_mul_f32 v[26:27], v[66:67], v[72:73] op_sel:[0,1] op_sel_hi:[1,1]
	v_cndmask_b32_e64 v34, v32, v33, s[6:7]
	v_cndmask_b32_e64 v35, v33, v32, s[6:7]
	v_pk_mul_f32 v[38:39], v[72:73], v[126:127] op_sel:[0,1] op_sel_hi:[1,1]
	v_pk_fma_f32 v[20:21], v[60:61], v[8:9], v[20:21] op_sel_hi:[1,0,1]
	v_add_f32_dpp v35, v34, v35 row_ror:8 row_mask:0xf bank_mask:0xf bound_ctrl:1
	v_pk_fma_f32 v[22:23], v[62:63], v[8:9], v[22:23] op_sel_hi:[1,0,1]
	v_pk_fma_f32 v[24:25], v[60:61], v[8:9], v[24:25] op_sel:[0,1,0] op_sel_hi:[1,1,1]
	v_pk_fma_f32 v[26:27], v[62:63], v[8:9], v[26:27] op_sel:[0,1,0] op_sel_hi:[1,1,1]
	v_add_f32_dpp v35, v35, v35 quad_perm:[1,0,3,2] row_mask:0xf bank_mask:0xf bound_ctrl:1
	v_pk_fma_f32 v[0:1], v[0:1], v[56:57], v[20:21]
	v_pk_fma_f32 v[2:3], v[2:3], v[58:59], v[22:23]
	v_pk_fma_f32 v[4:5], v[4:5], v[56:57], v[24:25]
	v_add_f32_dpp v35, v35, v35 quad_perm:[2,3,0,1] row_mask:0xf bank_mask:0xf bound_ctrl:1
	v_pk_fma_f32 v[6:7], v[6:7], v[58:59], v[26:27]
	v_pk_mul_f32 v[28:29], v[0:1], v[68:69]
	v_pk_fma_f32 v[38:39], v[8:9], v[126:127], v[38:39] op_sel_hi:[1,0,1]
	v_add_f32_dpp v35, v35, v35 row_half_mirror row_mask:0xf bank_mask:0xf bound_ctrl:1
	v_pk_mul_f32 v[30:31], v[4:5], v[68:69]
	v_pk_fma_f32 v[28:29], v[2:3], v[70:71], v[28:29]
	v_pk_fma_f32 v[30:31], v[6:7], v[70:71], v[30:31]
	v_mov_b32_dpp v34, v35 row_ror:8 row_mask:0xf bank_mask:0xf
	v_add_f32_e32 v16, v28, v29
	v_add_f32_e32 v17, v30, v31
	v_cndmask_b32_e64 v32, v34, v35, s[6:7]
	v_cndmask_b32_e64 v33, v35, v34, s[6:7]
	v_cndmask_b32_e64 v18, v16, v17, s[6:7]
	v_cndmask_b32_e64 v19, v17, v16, s[6:7]
	v_pk_add_f32 v[8:9], v[32:33], v[38:39] neg_lo:[1,1] neg_hi:[1,1]
	s_nop 0
	v_add_f32_dpp v36, v18, v19 row_ror:8 row_mask:0xf bank_mask:0xf bound_ctrl:1
	ds_write_b32 v13, v36 offset:2304
	s_waitcnt lgkmcnt(8)
	ds_read_b128 v[52:55], v10 offset:3072
	ds_read_b64 v[72:73], v11 offset:3072
	ds_read_b128 v[64:67], v10 offset:15360
	ds_read_b128 v[60:63], v10 offset:11264
	ds_read_b128 v[56:59], v10 offset:7168
	ds_read_b128 v[68:71], v10 offset:19456
	ds_read_b128 v[124:127], v12 offset:96
	v_pk_mul_f32 v[16:17], v[0:1], v[76:77]
	v_pk_mul_f32 v[18:19], v[4:5], v[76:77]
	v_pk_fma_f32 v[16:17], v[2:3], v[78:79], v[16:17]
	v_pk_fma_f32 v[18:19], v[6:7], v[78:79], v[18:19]
	v_pk_mul_f32 v[20:21], v[88:89], v[96:97] op_sel_hi:[1,0]
	v_pk_mul_f32 v[22:23], v[90:91], v[96:97] op_sel_hi:[1,0]
	v_add_f32_e32 v32, v16, v17
	v_add_f32_e32 v33, v18, v19
	v_pk_mul_f32 v[24:25], v[88:89], v[96:97] op_sel:[0,1] op_sel_hi:[1,1]
	v_pk_mul_f32 v[26:27], v[90:91], v[96:97] op_sel:[0,1] op_sel_hi:[1,1]
	v_cndmask_b32_e64 v34, v32, v33, s[6:7]
	v_cndmask_b32_e64 v35, v33, v32, s[6:7]
	v_pk_mul_f32 v[38:39], v[96:97], v[128:129] op_sel:[0,1] op_sel_hi:[1,1]
	v_pk_fma_f32 v[20:21], v[84:85], v[8:9], v[20:21] op_sel_hi:[1,0,1]
	v_add_f32_dpp v35, v34, v35 row_ror:8 row_mask:0xf bank_mask:0xf bound_ctrl:1
	v_pk_fma_f32 v[22:23], v[86:87], v[8:9], v[22:23] op_sel_hi:[1,0,1]
	v_pk_fma_f32 v[24:25], v[84:85], v[8:9], v[24:25] op_sel:[0,1,0] op_sel_hi:[1,1,1]
	v_pk_fma_f32 v[26:27], v[86:87], v[8:9], v[26:27] op_sel:[0,1,0] op_sel_hi:[1,1,1]
	v_add_f32_dpp v35, v35, v35 quad_perm:[1,0,3,2] row_mask:0xf bank_mask:0xf bound_ctrl:1
	v_pk_fma_f32 v[0:1], v[0:1], v[80:81], v[20:21]
	v_pk_fma_f32 v[2:3], v[2:3], v[82:83], v[22:23]
	v_pk_fma_f32 v[4:5], v[4:5], v[80:81], v[24:25]
	v_add_f32_dpp v35, v35, v35 quad_perm:[2,3,0,1] row_mask:0xf bank_mask:0xf bound_ctrl:1
	v_pk_fma_f32 v[6:7], v[6:7], v[82:83], v[26:27]
	v_pk_mul_f32 v[28:29], v[0:1], v[92:93]
	v_pk_fma_f32 v[38:39], v[8:9], v[128:129], v[38:39] op_sel_hi:[1,0,1]
	v_add_f32_dpp v35, v35, v35 row_half_mirror row_mask:0xf bank_mask:0xf bound_ctrl:1
	v_pk_mul_f32 v[30:31], v[4:5], v[92:93]
	v_pk_fma_f32 v[28:29], v[2:3], v[94:95], v[28:29]
	v_pk_fma_f32 v[30:31], v[6:7], v[94:95], v[30:31]
	v_mov_b32_dpp v34, v35 row_ror:8 row_mask:0xf bank_mask:0xf
	v_add_f32_e32 v16, v28, v29
	v_add_f32_e32 v17, v30, v31
	v_cndmask_b32_e64 v32, v34, v35, s[6:7]
	v_cndmask_b32_e64 v33, v35, v34, s[6:7]
	v_cndmask_b32_e64 v18, v16, v17, s[6:7]
	v_cndmask_b32_e64 v19, v17, v16, s[6:7]
	v_pk_add_f32 v[8:9], v[32:33], v[38:39] neg_lo:[1,1] neg_hi:[1,1]
	s_nop 0
	v_add_f32_dpp v36, v18, v19 row_ror:8 row_mask:0xf bank_mask:0xf bound_ctrl:1
	ds_write_b32 v13, v36 offset:2560
	s_waitcnt lgkmcnt(9)
	ds_read_b128 v[76:79], v10 offset:3328
	ds_read_b64 v[96:97], v11 offset:3328
	ds_read_b128 v[88:91], v10 offset:15616
	ds_read_b128 v[84:87], v10 offset:11520
	ds_read_b128 v[80:83], v10 offset:7424
	ds_read_b128 v[92:95], v10 offset:19712
	v_pk_mul_f32 v[16:17], v[0:1], v[100:101]
	v_pk_mul_f32 v[18:19], v[4:5], v[100:101]
	v_pk_fma_f32 v[16:17], v[2:3], v[102:103], v[16:17]
	v_pk_fma_f32 v[18:19], v[6:7], v[102:103], v[18:19]
	v_pk_mul_f32 v[20:21], v[112:113], v[120:121] op_sel_hi:[1,0]
	v_pk_mul_f32 v[22:23], v[114:115], v[120:121] op_sel_hi:[1,0]
	v_add_f32_e32 v32, v16, v17
	v_add_f32_e32 v33, v18, v19
	v_pk_mul_f32 v[24:25], v[112:113], v[120:121] op_sel:[0,1] op_sel_hi:[1,1]
	v_pk_mul_f32 v[26:27], v[114:115], v[120:121] op_sel:[0,1] op_sel_hi:[1,1]
	v_cndmask_b32_e64 v34, v32, v33, s[6:7]
	v_cndmask_b32_e64 v35, v33, v32, s[6:7]
	v_pk_mul_f32 v[38:39], v[120:121], v[130:131] op_sel:[0,1] op_sel_hi:[1,1]
	v_pk_fma_f32 v[20:21], v[108:109], v[8:9], v[20:21] op_sel_hi:[1,0,1]
	v_add_f32_dpp v35, v34, v35 row_ror:8 row_mask:0xf bank_mask:0xf bound_ctrl:1
	v_pk_fma_f32 v[22:23], v[110:111], v[8:9], v[22:23] op_sel_hi:[1,0,1]
	v_pk_fma_f32 v[24:25], v[108:109], v[8:9], v[24:25] op_sel:[0,1,0] op_sel_hi:[1,1,1]
	v_pk_fma_f32 v[26:27], v[110:111], v[8:9], v[26:27] op_sel:[0,1,0] op_sel_hi:[1,1,1]
	v_add_f32_dpp v35, v35, v35 quad_perm:[1,0,3,2] row_mask:0xf bank_mask:0xf bound_ctrl:1
	v_pk_fma_f32 v[0:1], v[0:1], v[104:105], v[20:21]
	v_pk_fma_f32 v[2:3], v[2:3], v[106:107], v[22:23]
	v_pk_fma_f32 v[4:5], v[4:5], v[104:105], v[24:25]
	v_add_f32_dpp v35, v35, v35 quad_perm:[2,3,0,1] row_mask:0xf bank_mask:0xf bound_ctrl:1
	v_pk_fma_f32 v[6:7], v[6:7], v[106:107], v[26:27]
	v_pk_mul_f32 v[28:29], v[0:1], v[116:117]
	v_pk_fma_f32 v[38:39], v[8:9], v[130:131], v[38:39] op_sel_hi:[1,0,1]
	v_add_f32_dpp v35, v35, v35 row_half_mirror row_mask:0xf bank_mask:0xf bound_ctrl:1
	v_pk_mul_f32 v[30:31], v[4:5], v[116:117]
	v_pk_fma_f32 v[28:29], v[2:3], v[118:119], v[28:29]
	v_pk_fma_f32 v[30:31], v[6:7], v[118:119], v[30:31]
	v_mov_b32_dpp v34, v35 row_ror:8 row_mask:0xf bank_mask:0xf
	v_add_f32_e32 v16, v28, v29
	v_add_f32_e32 v17, v30, v31
	v_cndmask_b32_e64 v32, v34, v35, s[6:7]
	v_cndmask_b32_e64 v33, v35, v34, s[6:7]
	v_cndmask_b32_e64 v18, v16, v17, s[6:7]
	v_cndmask_b32_e64 v19, v17, v16, s[6:7]
	v_pk_add_f32 v[8:9], v[32:33], v[38:39] neg_lo:[1,1] neg_hi:[1,1]
	s_nop 0
	v_add_f32_dpp v36, v18, v19 row_ror:8 row_mask:0xf bank_mask:0xf bound_ctrl:1
	ds_write_b32 v13, v36 offset:2816
	s_waitcnt lgkmcnt(8)
	ds_read_b128 v[100:103], v10 offset:3584
	ds_read_b64 v[120:121], v11 offset:3584
	ds_read_b128 v[112:115], v10 offset:15872
	ds_read_b128 v[108:111], v10 offset:11776
	ds_read_b128 v[104:107], v10 offset:7680
	ds_read_b128 v[116:119], v10 offset:19968
	ds_read_b128 v[128:131], v12 offset:112
	v_pk_mul_f32 v[16:17], v[0:1], v[52:53]
	v_pk_mul_f32 v[18:19], v[4:5], v[52:53]
	v_pk_fma_f32 v[16:17], v[2:3], v[54:55], v[16:17]
	v_pk_fma_f32 v[18:19], v[6:7], v[54:55], v[18:19]
	v_pk_mul_f32 v[20:21], v[64:65], v[72:73] op_sel_hi:[1,0]
	v_pk_mul_f32 v[22:23], v[66:67], v[72:73] op_sel_hi:[1,0]
	v_add_f32_e32 v32, v16, v17
	v_add_f32_e32 v33, v18, v19
	v_pk_mul_f32 v[24:25], v[64:65], v[72:73] op_sel:[0,1] op_sel_hi:[1,1]
	v_pk_mul_f32 v[26:27], v[66:67], v[72:73] op_sel:[0,1] op_sel_hi:[1,1]
	v_cndmask_b32_e64 v34, v32, v33, s[6:7]
	v_cndmask_b32_e64 v35, v33, v32, s[6:7]
	v_pk_mul_f32 v[38:39], v[72:73], v[124:125] op_sel:[0,1] op_sel_hi:[1,1]
	v_pk_fma_f32 v[20:21], v[60:61], v[8:9], v[20:21] op_sel_hi:[1,0,1]
	v_add_f32_dpp v35, v34, v35 row_ror:8 row_mask:0xf bank_mask:0xf bound_ctrl:1
	v_pk_fma_f32 v[22:23], v[62:63], v[8:9], v[22:23] op_sel_hi:[1,0,1]
	v_pk_fma_f32 v[24:25], v[60:61], v[8:9], v[24:25] op_sel:[0,1,0] op_sel_hi:[1,1,1]
	v_pk_fma_f32 v[26:27], v[62:63], v[8:9], v[26:27] op_sel:[0,1,0] op_sel_hi:[1,1,1]
	v_add_f32_dpp v35, v35, v35 quad_perm:[1,0,3,2] row_mask:0xf bank_mask:0xf bound_ctrl:1
	v_pk_fma_f32 v[0:1], v[0:1], v[56:57], v[20:21]
	v_pk_fma_f32 v[2:3], v[2:3], v[58:59], v[22:23]
	v_pk_fma_f32 v[4:5], v[4:5], v[56:57], v[24:25]
	v_add_f32_dpp v35, v35, v35 quad_perm:[2,3,0,1] row_mask:0xf bank_mask:0xf bound_ctrl:1
	v_pk_fma_f32 v[6:7], v[6:7], v[58:59], v[26:27]
	v_pk_mul_f32 v[28:29], v[0:1], v[68:69]
	v_pk_fma_f32 v[38:39], v[8:9], v[124:125], v[38:39] op_sel_hi:[1,0,1]
	v_add_f32_dpp v35, v35, v35 row_half_mirror row_mask:0xf bank_mask:0xf bound_ctrl:1
	v_pk_mul_f32 v[30:31], v[4:5], v[68:69]
	v_pk_fma_f32 v[28:29], v[2:3], v[70:71], v[28:29]
	v_pk_fma_f32 v[30:31], v[6:7], v[70:71], v[30:31]
	v_mov_b32_dpp v34, v35 row_ror:8 row_mask:0xf bank_mask:0xf
	v_add_f32_e32 v16, v28, v29
	v_add_f32_e32 v17, v30, v31
	v_cndmask_b32_e64 v32, v34, v35, s[6:7]
	v_cndmask_b32_e64 v33, v35, v34, s[6:7]
	v_cndmask_b32_e64 v18, v16, v17, s[6:7]
	v_cndmask_b32_e64 v19, v17, v16, s[6:7]
	v_pk_add_f32 v[8:9], v[32:33], v[38:39] neg_lo:[1,1] neg_hi:[1,1]
	s_nop 0
	v_add_f32_dpp v36, v18, v19 row_ror:8 row_mask:0xf bank_mask:0xf bound_ctrl:1
	ds_write_b32 v13, v36 offset:3072
	s_waitcnt lgkmcnt(9)
	ds_read_b128 v[52:55], v10 offset:3840
	ds_read_b64 v[72:73], v11 offset:3840
	ds_read_b128 v[64:67], v10 offset:16128
	ds_read_b128 v[60:63], v10 offset:12032
	ds_read_b128 v[56:59], v10 offset:7936
	ds_read_b128 v[68:71], v10 offset:20224
	v_pk_mul_f32 v[16:17], v[0:1], v[76:77]
	v_pk_mul_f32 v[18:19], v[4:5], v[76:77]
	v_pk_fma_f32 v[16:17], v[2:3], v[78:79], v[16:17]
	v_pk_fma_f32 v[18:19], v[6:7], v[78:79], v[18:19]
	v_pk_mul_f32 v[20:21], v[88:89], v[96:97] op_sel_hi:[1,0]
	v_pk_mul_f32 v[22:23], v[90:91], v[96:97] op_sel_hi:[1,0]
	v_add_f32_e32 v32, v16, v17
	v_add_f32_e32 v33, v18, v19
	v_pk_mul_f32 v[24:25], v[88:89], v[96:97] op_sel:[0,1] op_sel_hi:[1,1]
	v_pk_mul_f32 v[26:27], v[90:91], v[96:97] op_sel:[0,1] op_sel_hi:[1,1]
	v_cndmask_b32_e64 v34, v32, v33, s[6:7]
	v_cndmask_b32_e64 v35, v33, v32, s[6:7]
	v_pk_mul_f32 v[38:39], v[96:97], v[126:127] op_sel:[0,1] op_sel_hi:[1,1]
	v_pk_fma_f32 v[20:21], v[84:85], v[8:9], v[20:21] op_sel_hi:[1,0,1]
	v_add_f32_dpp v35, v34, v35 row_ror:8 row_mask:0xf bank_mask:0xf bound_ctrl:1
	v_pk_fma_f32 v[22:23], v[86:87], v[8:9], v[22:23] op_sel_hi:[1,0,1]
	v_pk_fma_f32 v[24:25], v[84:85], v[8:9], v[24:25] op_sel:[0,1,0] op_sel_hi:[1,1,1]
	v_pk_fma_f32 v[26:27], v[86:87], v[8:9], v[26:27] op_sel:[0,1,0] op_sel_hi:[1,1,1]
	v_add_f32_dpp v35, v35, v35 quad_perm:[1,0,3,2] row_mask:0xf bank_mask:0xf bound_ctrl:1
	v_pk_fma_f32 v[0:1], v[0:1], v[80:81], v[20:21]
	v_pk_fma_f32 v[2:3], v[2:3], v[82:83], v[22:23]
	v_pk_fma_f32 v[4:5], v[4:5], v[80:81], v[24:25]
	v_add_f32_dpp v35, v35, v35 quad_perm:[2,3,0,1] row_mask:0xf bank_mask:0xf bound_ctrl:1
	v_pk_fma_f32 v[6:7], v[6:7], v[82:83], v[26:27]
	v_pk_mul_f32 v[28:29], v[0:1], v[92:93]
	v_pk_fma_f32 v[38:39], v[8:9], v[126:127], v[38:39] op_sel_hi:[1,0,1]
	v_add_f32_dpp v35, v35, v35 row_half_mirror row_mask:0xf bank_mask:0xf bound_ctrl:1
	v_pk_mul_f32 v[30:31], v[4:5], v[92:93]
	v_pk_fma_f32 v[28:29], v[2:3], v[94:95], v[28:29]
	v_pk_fma_f32 v[30:31], v[6:7], v[94:95], v[30:31]
	v_mov_b32_dpp v34, v35 row_ror:8 row_mask:0xf bank_mask:0xf
	v_add_f32_e32 v16, v28, v29
	v_add_f32_e32 v17, v30, v31
	v_cndmask_b32_e64 v32, v34, v35, s[6:7]
	v_cndmask_b32_e64 v33, v35, v34, s[6:7]
	v_cndmask_b32_e64 v18, v16, v17, s[6:7]
	v_cndmask_b32_e64 v19, v17, v16, s[6:7]
	v_pk_add_f32 v[8:9], v[32:33], v[38:39] neg_lo:[1,1] neg_hi:[1,1]
	s_nop 0
	v_add_f32_dpp v36, v18, v19 row_ror:8 row_mask:0xf bank_mask:0xf bound_ctrl:1
	ds_write_b32 v13, v36 offset:3328
	s_waitcnt lgkmcnt(8)
	v_pk_mul_f32 v[16:17], v[0:1], v[100:101]
	v_pk_mul_f32 v[18:19], v[4:5], v[100:101]
	v_pk_fma_f32 v[16:17], v[2:3], v[102:103], v[16:17]
	v_pk_fma_f32 v[18:19], v[6:7], v[102:103], v[18:19]
	v_pk_mul_f32 v[20:21], v[112:113], v[120:121] op_sel_hi:[1,0]
	v_pk_mul_f32 v[22:23], v[114:115], v[120:121] op_sel_hi:[1,0]
	v_add_f32_e32 v32, v16, v17
	v_add_f32_e32 v33, v18, v19
	v_pk_mul_f32 v[24:25], v[112:113], v[120:121] op_sel:[0,1] op_sel_hi:[1,1]
	v_pk_mul_f32 v[26:27], v[114:115], v[120:121] op_sel:[0,1] op_sel_hi:[1,1]
	v_cndmask_b32_e64 v34, v32, v33, s[6:7]
	v_cndmask_b32_e64 v35, v33, v32, s[6:7]
	v_pk_mul_f32 v[38:39], v[120:121], v[128:129] op_sel:[0,1] op_sel_hi:[1,1]
	v_pk_fma_f32 v[20:21], v[108:109], v[8:9], v[20:21] op_sel_hi:[1,0,1]
	v_add_f32_dpp v35, v34, v35 row_ror:8 row_mask:0xf bank_mask:0xf bound_ctrl:1
	v_pk_fma_f32 v[22:23], v[110:111], v[8:9], v[22:23] op_sel_hi:[1,0,1]
	v_pk_fma_f32 v[24:25], v[108:109], v[8:9], v[24:25] op_sel:[0,1,0] op_sel_hi:[1,1,1]
	v_pk_fma_f32 v[26:27], v[110:111], v[8:9], v[26:27] op_sel:[0,1,0] op_sel_hi:[1,1,1]
	v_add_f32_dpp v35, v35, v35 quad_perm:[1,0,3,2] row_mask:0xf bank_mask:0xf bound_ctrl:1
	v_pk_fma_f32 v[0:1], v[0:1], v[104:105], v[20:21]
	v_pk_fma_f32 v[2:3], v[2:3], v[106:107], v[22:23]
	v_pk_fma_f32 v[4:5], v[4:5], v[104:105], v[24:25]
	v_add_f32_dpp v35, v35, v35 quad_perm:[2,3,0,1] row_mask:0xf bank_mask:0xf bound_ctrl:1
	v_pk_fma_f32 v[6:7], v[6:7], v[106:107], v[26:27]
	v_pk_mul_f32 v[28:29], v[0:1], v[116:117]
	v_pk_fma_f32 v[38:39], v[8:9], v[128:129], v[38:39] op_sel_hi:[1,0,1]
	v_add_f32_dpp v35, v35, v35 row_half_mirror row_mask:0xf bank_mask:0xf bound_ctrl:1
	v_pk_mul_f32 v[30:31], v[4:5], v[116:117]
	v_pk_fma_f32 v[28:29], v[2:3], v[118:119], v[28:29]
	v_pk_fma_f32 v[30:31], v[6:7], v[118:119], v[30:31]
	v_mov_b32_dpp v34, v35 row_ror:8 row_mask:0xf bank_mask:0xf
	v_add_f32_e32 v16, v28, v29
	v_add_f32_e32 v17, v30, v31
	v_cndmask_b32_e64 v32, v34, v35, s[6:7]
	v_cndmask_b32_e64 v33, v35, v34, s[6:7]
	v_cndmask_b32_e64 v18, v16, v17, s[6:7]
	v_cndmask_b32_e64 v19, v17, v16, s[6:7]
	v_pk_add_f32 v[8:9], v[32:33], v[38:39] neg_lo:[1,1] neg_hi:[1,1]
	s_nop 0
	v_add_f32_dpp v36, v18, v19 row_ror:8 row_mask:0xf bank_mask:0xf bound_ctrl:1
	ds_write_b32 v13, v36 offset:3584
	s_waitcnt lgkmcnt(2)
	v_pk_mul_f32 v[16:17], v[0:1], v[52:53]
	v_pk_mul_f32 v[18:19], v[4:5], v[52:53]
	v_pk_fma_f32 v[16:17], v[2:3], v[54:55], v[16:17]
	v_pk_fma_f32 v[18:19], v[6:7], v[54:55], v[18:19]
	v_pk_mul_f32 v[20:21], v[64:65], v[72:73] op_sel_hi:[1,0]
	v_pk_mul_f32 v[22:23], v[66:67], v[72:73] op_sel_hi:[1,0]
	v_add_f32_e32 v32, v16, v17
	v_add_f32_e32 v33, v18, v19
	v_pk_mul_f32 v[24:25], v[64:65], v[72:73] op_sel:[0,1] op_sel_hi:[1,1]
	v_pk_mul_f32 v[26:27], v[66:67], v[72:73] op_sel:[0,1] op_sel_hi:[1,1]
	v_cndmask_b32_e64 v34, v32, v33, s[6:7]
	v_cndmask_b32_e64 v35, v33, v32, s[6:7]
	v_pk_mul_f32 v[38:39], v[72:73], v[130:131] op_sel:[0,1] op_sel_hi:[1,1]
	v_pk_fma_f32 v[20:21], v[60:61], v[8:9], v[20:21] op_sel_hi:[1,0,1]
	v_add_f32_dpp v35, v34, v35 row_ror:8 row_mask:0xf bank_mask:0xf bound_ctrl:1
	v_pk_fma_f32 v[22:23], v[62:63], v[8:9], v[22:23] op_sel_hi:[1,0,1]
	v_pk_fma_f32 v[24:25], v[60:61], v[8:9], v[24:25] op_sel:[0,1,0] op_sel_hi:[1,1,1]
	v_pk_fma_f32 v[26:27], v[62:63], v[8:9], v[26:27] op_sel:[0,1,0] op_sel_hi:[1,1,1]
	v_add_f32_dpp v35, v35, v35 quad_perm:[1,0,3,2] row_mask:0xf bank_mask:0xf bound_ctrl:1
	v_pk_fma_f32 v[0:1], v[0:1], v[56:57], v[20:21]
	v_pk_fma_f32 v[2:3], v[2:3], v[58:59], v[22:23]
	v_pk_fma_f32 v[4:5], v[4:5], v[56:57], v[24:25]
	v_add_f32_dpp v35, v35, v35 quad_perm:[2,3,0,1] row_mask:0xf bank_mask:0xf bound_ctrl:1
	v_pk_fma_f32 v[6:7], v[6:7], v[58:59], v[26:27]
	v_pk_mul_f32 v[28:29], v[0:1], v[68:69]
	v_pk_fma_f32 v[38:39], v[8:9], v[130:131], v[38:39] op_sel_hi:[1,0,1]
	v_add_f32_dpp v35, v35, v35 row_half_mirror row_mask:0xf bank_mask:0xf bound_ctrl:1
	v_pk_mul_f32 v[30:31], v[4:5], v[68:69]
	v_pk_fma_f32 v[28:29], v[2:3], v[70:71], v[28:29]
	v_pk_fma_f32 v[30:31], v[6:7], v[70:71], v[30:31]
	v_mov_b32_dpp v34, v35 row_ror:8 row_mask:0xf bank_mask:0xf
	v_add_f32_e32 v16, v28, v29
	v_add_f32_e32 v17, v30, v31
	v_cndmask_b32_e64 v32, v34, v35, s[6:7]
	v_cndmask_b32_e64 v33, v35, v34, s[6:7]
	v_cndmask_b32_e64 v18, v16, v17, s[6:7]
	v_cndmask_b32_e64 v19, v17, v16, s[6:7]
	v_pk_add_f32 v[8:9], v[32:33], v[38:39] neg_lo:[1,1] neg_hi:[1,1]
	s_nop 0
	v_add_f32_dpp v36, v18, v19 row_ror:8 row_mask:0xf bank_mask:0xf bound_ctrl:1
	ds_write_b32 v13, v36 offset:3840
	s_add_i32 s0, s0, 1
	s_waitcnt lgkmcnt(0)
	s_barrier
	s_cmpk_eq_i32 s0, 0x100
	s_cbranch_scc0 .Lsc_chunk
	s_setprio 0
	s_cmp_lg_u32 s14, 0
	s_cbranch_scc1 .LBB0_674
	v_readlane_b32 s0, v253, 16
	v_readlane_b32 s1, v253, 17
	s_nop 3
	s_add_u32 s0, s0, 0xec00000
	s_addc_u32 s1, s1, 0
	s_nop 3
	global_store_dwordx4 v49, v[0:3], s[0:1]
	global_store_dwordx4 v49, v[4:7], s[0:1] offset:256
